# speedup vs baseline: 1.0065x; 1.0013x over previous
.LBB0_849:
	v_lshl_or_b32 v158, s30, 8, v164
	v_readlane_b32 s0, v253, 50
	v_ashrrev_i32_e32 v159, 31, v158
	v_readlane_b32 s1, v253, 51
	v_lshl_add_u32 v160, s29, 8, v162
	v_ashrrev_i32_e32 v161, 31, v160
	v_lshl_add_u64 v[156:157], v[158:159], 2, s[0:1]
	global_load_dwordx4 v[140:143], v[156:157], off offset:16
	global_load_dwordx4 v[144:147], v[156:157], off
	v_readlane_b32 s0, v253, 58
	v_readlane_b32 s1, v253, 59
	s_mov_b64 s[18:19], 0x40000
	s_andn2_b64 vcc, exec, s[4:5]
	s_mov_b32 s44, 0x8000
	s_mov_b32 s45, 0xa000
	s_waitcnt vmcnt(0)
	v_pk_add_f32 v[148:149], v[142:143], 1.0 op_sel_hi:[1,0]
	v_pk_add_f32 v[150:151], v[140:141], 1.0 op_sel_hi:[1,0]
	global_load_dwordx4 v[166:169], v[156:157], off offset:528
	global_load_dwordx4 v[140:143], v[156:157], off offset:512
	v_lshlrev_b64 v[156:157], 11, v[160:161]
	v_lshl_add_u64 v[156:157], v[156:157], 0, v[158:159]
	v_lshl_add_u64 v[174:175], v[156:157], 2, s[0:1]
	v_pk_add_f32 v[152:153], v[146:147], 1.0 op_sel_hi:[1,0]
	v_pk_add_f32 v[154:155], v[144:145], 1.0 op_sel_hi:[1,0]
	s_waitcnt vmcnt(0)
	v_pk_add_f32 v[144:145], v[142:143], 1.0 op_sel_hi:[1,0]
	v_pk_add_f32 v[146:147], v[140:141], 1.0 op_sel_hi:[1,0]
	v_pk_add_f32 v[140:141], v[168:169], 1.0 op_sel_hi:[1,0]
	v_pk_add_f32 v[142:143], v[166:167], 1.0 op_sel_hi:[1,0]
	v_lshlrev_b32_e32 v184, 2, v156
	v_readlane_b32 s100, v253, 58
	v_readlane_b32 s101, v253, 59
	s_nop 1
	s_add_u32 s100, s100, 0x0
	s_addc_u32 s101, s101, 0
	global_load_dwordx4 v[176:179], v184, s[100:101] offset:16
	global_load_dwordx4 v[180:183], v184, s[100:101] offset:0
	global_load_dwordx4 v[188:191], v184, s[100:101] offset:528
	global_load_dwordx4 v[192:195], v184, s[100:101] offset:512
	s_add_u32 s100, s100, 0x20000
	s_addc_u32 s101, s101, 0
	global_load_dwordx4 v[196:199], v184, s[100:101] offset:16
	global_load_dwordx4 v[200:203], v184, s[100:101] offset:0
	global_load_dwordx4 v[204:207], v184, s[100:101] offset:528
	global_load_dwordx4 v[218:221], v184, s[100:101] offset:512
	s_waitcnt vmcnt(0)
	v_pk_mul_f32 v[168:169], v[178:179], s[60:61] op_sel_hi:[1,0]
	v_pk_mul_f32 v[172:173], v[182:183], s[60:61] op_sel_hi:[1,0]
	v_pk_mul_f32 v[170:171], v[180:181], s[60:61] op_sel_hi:[1,0]
	v_pk_mul_f32 v[166:167], v[176:177], s[60:61] op_sel_hi:[1,0]
	v_pk_fma_f32 v[128:129], v[128:129], v[152:153], v[172:173]
	v_pk_fma_f32 v[126:127], v[126:127], v[154:155], v[170:171]
	v_pk_fma_f32 v[168:169], v[124:125], v[148:149], v[168:169]
	v_pk_fma_f32 v[124:125], v[122:123], v[150:151], v[166:167]
	v_lshlrev_b64 v[166:167], 1, v[156:157]
	v_cvt_pk_bf16_f32 v122, v126, v127
	v_cvt_pk_bf16_f32 v123, v128, v129
	v_cvt_pk_bf16_f32 v124, v124, v125
	v_cvt_pk_bf16_f32 v125, v168, v169
	v_lshl_add_u64 v[126:127], s[50:51], 0, v[166:167]
	global_store_dwordx4 v[126:127], v[122:125], off
	s_nop 0
	v_or_b32_e32 v166, 0x100, v166
	v_pk_mul_f32 v[124:125], v[190:191], s[60:61] op_sel_hi:[1,0]
	v_pk_mul_f32 v[128:129], v[194:195], s[60:61] op_sel_hi:[1,0]
	v_pk_mul_f32 v[126:127], v[192:193], s[60:61] op_sel_hi:[1,0]
	v_pk_mul_f32 v[122:123], v[188:189], s[60:61] op_sel_hi:[1,0]
	v_pk_fma_f32 v[120:121], v[120:121], v[144:145], v[128:129]
	v_pk_fma_f32 v[118:119], v[118:119], v[146:147], v[126:127]
	v_pk_fma_f32 v[124:125], v[116:117], v[140:141], v[124:125]
	v_pk_fma_f32 v[116:117], v[114:115], v[142:143], v[122:123]
	v_cvt_pk_bf16_f32 v114, v118, v119
	v_cvt_pk_bf16_f32 v115, v120, v121
	v_cvt_pk_bf16_f32 v116, v116, v117
	v_cvt_pk_bf16_f32 v117, v124, v125
	v_lshl_add_u64 v[118:119], s[50:51], 0, v[166:167]
	global_store_dwordx4 v[118:119], v[114:117], off
	s_nop 1
	v_or_b32_e32 v114, 16, v160
	v_ashrrev_i32_e32 v115, 31, v114
	v_lshlrev_b64 v[114:115], 11, v[114:115]
	v_lshl_add_u64 v[122:123], v[114:115], 0, v[158:159]
	v_lshl_add_u64 v[124:125], v[122:123], 2, s[0:1]
	v_pk_mul_f32 v[116:117], v[198:199], s[60:61] op_sel_hi:[1,0]
	v_pk_mul_f32 v[120:121], v[202:203], s[60:61] op_sel_hi:[1,0]
	v_pk_mul_f32 v[118:119], v[200:201], s[60:61] op_sel_hi:[1,0]
	v_pk_mul_f32 v[114:115], v[196:197], s[60:61] op_sel_hi:[1,0]
	v_pk_fma_f32 v[112:113], v[112:113], v[152:153], v[120:121]
	v_pk_fma_f32 v[110:111], v[110:111], v[154:155], v[118:119]
	v_pk_fma_f32 v[116:117], v[108:109], v[148:149], v[116:117]
	v_pk_fma_f32 v[108:109], v[106:107], v[150:151], v[114:115]
	v_lshlrev_b64 v[114:115], 1, v[122:123]
	v_cvt_pk_bf16_f32 v106, v110, v111
	v_cvt_pk_bf16_f32 v107, v112, v113
	v_cvt_pk_bf16_f32 v108, v108, v109
	v_cvt_pk_bf16_f32 v109, v116, v117
	v_lshl_add_u64 v[110:111], s[50:51], 0, v[114:115]
	global_store_dwordx4 v[110:111], v[106:109], off
	s_nop 0
	v_or_b32_e32 v114, 0x100, v114
	v_pk_mul_f32 v[108:109], v[206:207], s[60:61] op_sel_hi:[1,0]
	v_pk_mul_f32 v[112:113], v[220:221], s[60:61] op_sel_hi:[1,0]
	v_pk_mul_f32 v[110:111], v[218:219], s[60:61] op_sel_hi:[1,0]
	v_pk_mul_f32 v[106:107], v[204:205], s[60:61] op_sel_hi:[1,0]
	v_pk_fma_f32 v[104:105], v[104:105], v[144:145], v[112:113]
	v_pk_fma_f32 v[102:103], v[102:103], v[146:147], v[110:111]
	v_pk_fma_f32 v[108:109], v[100:101], v[140:141], v[108:109]
	v_pk_fma_f32 v[100:101], v[98:99], v[142:143], v[106:107]
	v_cvt_pk_bf16_f32 v98, v102, v103
	v_cvt_pk_bf16_f32 v99, v104, v105
	v_cvt_pk_bf16_f32 v100, v100, v101
	v_cvt_pk_bf16_f32 v101, v108, v109
	v_lshl_add_u64 v[102:103], s[50:51], 0, v[114:115]
	global_store_dwordx4 v[102:103], v[98:101], off
	s_nop 1
	v_or_b32_e32 v98, 32, v160
	v_ashrrev_i32_e32 v99, 31, v98
	v_lshlrev_b64 v[98:99], 11, v[98:99]
	v_lshl_add_u64 v[106:107], v[98:99], 0, v[158:159]
	v_lshl_add_u64 v[108:109], v[106:107], 2, s[0:1]
	v_lshlrev_b32_e32 v184, 2, v156
	v_readlane_b32 s100, v253, 58
	v_readlane_b32 s101, v253, 59
	s_nop 1
	s_add_u32 s100, s100, 0x40000
	s_addc_u32 s101, s101, 0
	global_load_dwordx4 v[176:179], v184, s[100:101] offset:16
	global_load_dwordx4 v[180:183], v184, s[100:101] offset:0
	global_load_dwordx4 v[188:191], v184, s[100:101] offset:528
	global_load_dwordx4 v[192:195], v184, s[100:101] offset:512
	s_add_u32 s100, s100, 0x20000
	s_addc_u32 s101, s101, 0
	global_load_dwordx4 v[196:199], v184, s[100:101] offset:16
	global_load_dwordx4 v[200:203], v184, s[100:101] offset:0
	global_load_dwordx4 v[204:207], v184, s[100:101] offset:528
	global_load_dwordx4 v[218:221], v184, s[100:101] offset:512
	s_waitcnt vmcnt(0)
	v_pk_mul_f32 v[100:101], v[178:179], s[60:61] op_sel_hi:[1,0]
	v_pk_mul_f32 v[104:105], v[182:183], s[60:61] op_sel_hi:[1,0]
	v_pk_mul_f32 v[102:103], v[180:181], s[60:61] op_sel_hi:[1,0]
	v_pk_mul_f32 v[98:99], v[176:177], s[60:61] op_sel_hi:[1,0]
	v_pk_fma_f32 v[96:97], v[96:97], v[152:153], v[104:105]
	v_pk_fma_f32 v[94:95], v[94:95], v[154:155], v[102:103]
	v_pk_fma_f32 v[100:101], v[92:93], v[148:149], v[100:101]
	v_pk_fma_f32 v[92:93], v[90:91], v[150:151], v[98:99]
	v_lshlrev_b64 v[98:99], 1, v[106:107]
	v_cvt_pk_bf16_f32 v90, v94, v95
	v_cvt_pk_bf16_f32 v91, v96, v97
	v_cvt_pk_bf16_f32 v92, v92, v93
	v_cvt_pk_bf16_f32 v93, v100, v101
	v_lshl_add_u64 v[94:95], s[50:51], 0, v[98:99]
	global_store_dwordx4 v[94:95], v[90:93], off
	s_nop 0
	v_or_b32_e32 v98, 0x100, v98
	v_pk_mul_f32 v[92:93], v[190:191], s[60:61] op_sel_hi:[1,0]
	v_pk_mul_f32 v[96:97], v[194:195], s[60:61] op_sel_hi:[1,0]
	v_pk_mul_f32 v[94:95], v[192:193], s[60:61] op_sel_hi:[1,0]
	v_pk_mul_f32 v[90:91], v[188:189], s[60:61] op_sel_hi:[1,0]
	v_pk_fma_f32 v[88:89], v[88:89], v[144:145], v[96:97]
	v_pk_fma_f32 v[86:87], v[86:87], v[146:147], v[94:95]
	v_pk_fma_f32 v[92:93], v[84:85], v[140:141], v[92:93]
	v_pk_fma_f32 v[84:85], v[82:83], v[142:143], v[90:91]
	v_cvt_pk_bf16_f32 v82, v86, v87
	v_cvt_pk_bf16_f32 v83, v88, v89
	v_cvt_pk_bf16_f32 v84, v84, v85
	v_cvt_pk_bf16_f32 v85, v92, v93
	v_lshl_add_u64 v[86:87], s[50:51], 0, v[98:99]
	global_store_dwordx4 v[86:87], v[82:85], off
	s_nop 1
	v_or_b32_e32 v82, 48, v160
	v_ashrrev_i32_e32 v83, 31, v82
	v_lshlrev_b64 v[82:83], 11, v[82:83]
	v_lshl_add_u64 v[90:91], v[82:83], 0, v[158:159]
	v_lshl_add_u64 v[92:93], v[90:91], 2, s[0:1]
	v_pk_mul_f32 v[84:85], v[198:199], s[60:61] op_sel_hi:[1,0]
	v_pk_mul_f32 v[88:89], v[202:203], s[60:61] op_sel_hi:[1,0]
	v_pk_mul_f32 v[86:87], v[200:201], s[60:61] op_sel_hi:[1,0]
	v_pk_mul_f32 v[82:83], v[196:197], s[60:61] op_sel_hi:[1,0]
	v_pk_fma_f32 v[80:81], v[80:81], v[152:153], v[88:89]
	v_pk_fma_f32 v[78:79], v[78:79], v[154:155], v[86:87]
	v_pk_fma_f32 v[84:85], v[76:77], v[148:149], v[84:85]
	v_pk_fma_f32 v[76:77], v[74:75], v[150:151], v[82:83]
	v_lshlrev_b64 v[82:83], 1, v[90:91]
	v_cvt_pk_bf16_f32 v74, v78, v79
	v_cvt_pk_bf16_f32 v75, v80, v81
	v_cvt_pk_bf16_f32 v76, v76, v77
	v_cvt_pk_bf16_f32 v77, v84, v85
	v_lshl_add_u64 v[78:79], s[50:51], 0, v[82:83]
	global_store_dwordx4 v[78:79], v[74:77], off
	s_nop 0
	v_or_b32_e32 v82, 0x100, v82
	v_pk_mul_f32 v[76:77], v[206:207], s[60:61] op_sel_hi:[1,0]
	v_pk_mul_f32 v[80:81], v[220:221], s[60:61] op_sel_hi:[1,0]
	v_pk_mul_f32 v[78:79], v[218:219], s[60:61] op_sel_hi:[1,0]
	v_pk_mul_f32 v[74:75], v[204:205], s[60:61] op_sel_hi:[1,0]
	v_pk_fma_f32 v[72:73], v[72:73], v[144:145], v[80:81]
	v_pk_fma_f32 v[70:71], v[70:71], v[146:147], v[78:79]
	v_pk_fma_f32 v[76:77], v[68:69], v[140:141], v[76:77]
	v_pk_fma_f32 v[68:69], v[66:67], v[142:143], v[74:75]
	v_cvt_pk_bf16_f32 v66, v70, v71
	v_cvt_pk_bf16_f32 v67, v72, v73
	v_cvt_pk_bf16_f32 v68, v68, v69
	v_cvt_pk_bf16_f32 v69, v76, v77
	v_lshl_add_u64 v[70:71], s[50:51], 0, v[82:83]
	v_lshl_add_u64 v[74:75], v[156:157], 0, s[18:19]
	global_store_dwordx4 v[70:71], v[66:69], off
	v_lshl_add_u64 v[76:77], v[74:75], 2, s[0:1]
	v_lshlrev_b32_e32 v184, 2, v156
	v_readlane_b32 s100, v253, 58
	v_readlane_b32 s101, v253, 59
	s_nop 1
	s_add_u32 s100, s100, 0x100000
	s_addc_u32 s101, s101, 0
	global_load_dwordx4 v[176:179], v184, s[100:101] offset:16
	global_load_dwordx4 v[180:183], v184, s[100:101] offset:0
	global_load_dwordx4 v[188:191], v184, s[100:101] offset:528
	global_load_dwordx4 v[192:195], v184, s[100:101] offset:512
	s_add_u32 s100, s100, 0x20000
	s_addc_u32 s101, s101, 0
	global_load_dwordx4 v[196:199], v184, s[100:101] offset:16
	global_load_dwordx4 v[200:203], v184, s[100:101] offset:0
	global_load_dwordx4 v[204:207], v184, s[100:101] offset:528
	global_load_dwordx4 v[218:221], v184, s[100:101] offset:512
	s_waitcnt vmcnt(0)
	s_mov_b64 s[18:19], 0x48000
	v_pk_mul_f32 v[68:69], v[178:179], s[60:61] op_sel_hi:[1,0]
	v_pk_mul_f32 v[72:73], v[182:183], s[60:61] op_sel_hi:[1,0]
	v_pk_mul_f32 v[70:71], v[180:181], s[60:61] op_sel_hi:[1,0]
	v_pk_mul_f32 v[66:67], v[176:177], s[60:61] op_sel_hi:[1,0]
	v_pk_fma_f32 v[64:65], v[64:65], v[152:153], v[72:73]
	v_pk_fma_f32 v[62:63], v[62:63], v[154:155], v[70:71]
	v_pk_fma_f32 v[68:69], v[60:61], v[148:149], v[68:69]
	v_pk_fma_f32 v[60:61], v[58:59], v[150:151], v[66:67]
	v_lshlrev_b64 v[66:67], 1, v[74:75]
	v_cvt_pk_bf16_f32 v58, v62, v63
	v_cvt_pk_bf16_f32 v59, v64, v65
	v_cvt_pk_bf16_f32 v60, v60, v61
	v_cvt_pk_bf16_f32 v61, v68, v69
	v_lshl_add_u64 v[62:63], s[50:51], 0, v[66:67]
	global_store_dwordx4 v[62:63], v[58:61], off
	s_nop 0
	v_or_b32_e32 v66, 0x100, v66
	v_pk_mul_f32 v[60:61], v[190:191], s[60:61] op_sel_hi:[1,0]
	v_pk_mul_f32 v[64:65], v[194:195], s[60:61] op_sel_hi:[1,0]
	v_pk_mul_f32 v[62:63], v[192:193], s[60:61] op_sel_hi:[1,0]
	v_pk_mul_f32 v[58:59], v[188:189], s[60:61] op_sel_hi:[1,0]
	v_pk_fma_f32 v[56:57], v[56:57], v[144:145], v[64:65]
	v_pk_fma_f32 v[54:55], v[54:55], v[146:147], v[62:63]
	v_pk_fma_f32 v[60:61], v[52:53], v[140:141], v[60:61]
	v_pk_fma_f32 v[52:53], v[50:51], v[142:143], v[58:59]
	v_cvt_pk_bf16_f32 v50, v54, v55
	v_cvt_pk_bf16_f32 v51, v56, v57
	v_cvt_pk_bf16_f32 v52, v52, v53
	v_cvt_pk_bf16_f32 v53, v60, v61
	v_lshl_add_u64 v[54:55], s[50:51], 0, v[66:67]
	v_lshl_add_u64 v[58:59], v[156:157], 0, s[18:19]
	global_store_dwordx4 v[54:55], v[50:53], off
	v_lshl_add_u64 v[60:61], v[58:59], 2, s[0:1]
	s_mov_b64 s[18:19], 0x50000
	v_pk_mul_f32 v[52:53], v[198:199], s[60:61] op_sel_hi:[1,0]
	v_pk_mul_f32 v[56:57], v[202:203], s[60:61] op_sel_hi:[1,0]
	v_pk_mul_f32 v[54:55], v[200:201], s[60:61] op_sel_hi:[1,0]
	v_pk_mul_f32 v[50:51], v[196:197], s[60:61] op_sel_hi:[1,0]
	v_pk_fma_f32 v[48:49], v[48:49], v[152:153], v[56:57]
	v_pk_fma_f32 v[46:47], v[46:47], v[154:155], v[54:55]
	v_pk_fma_f32 v[52:53], v[44:45], v[148:149], v[52:53]
	v_pk_fma_f32 v[44:45], v[42:43], v[150:151], v[50:51]
	v_lshlrev_b64 v[50:51], 1, v[58:59]
	v_cvt_pk_bf16_f32 v42, v46, v47
	v_cvt_pk_bf16_f32 v43, v48, v49
	v_cvt_pk_bf16_f32 v44, v44, v45
	v_cvt_pk_bf16_f32 v45, v52, v53
	v_lshl_add_u64 v[46:47], s[50:51], 0, v[50:51]
	global_store_dwordx4 v[46:47], v[42:45], off
	s_nop 0
	v_or_b32_e32 v50, 0x100, v50
	v_pk_mul_f32 v[44:45], v[206:207], s[60:61] op_sel_hi:[1,0]
	v_pk_mul_f32 v[48:49], v[220:221], s[60:61] op_sel_hi:[1,0]
	v_pk_mul_f32 v[46:47], v[218:219], s[60:61] op_sel_hi:[1,0]
	v_pk_mul_f32 v[42:43], v[204:205], s[60:61] op_sel_hi:[1,0]
	v_pk_fma_f32 v[40:41], v[40:41], v[144:145], v[48:49]
	v_pk_fma_f32 v[38:39], v[38:39], v[146:147], v[46:47]
	v_pk_fma_f32 v[44:45], v[36:37], v[140:141], v[44:45]
	v_pk_fma_f32 v[36:37], v[34:35], v[142:143], v[42:43]
	v_cvt_pk_bf16_f32 v34, v38, v39
	v_cvt_pk_bf16_f32 v35, v40, v41
	v_cvt_pk_bf16_f32 v36, v36, v37
	v_cvt_pk_bf16_f32 v37, v44, v45
	v_lshl_add_u64 v[38:39], s[50:51], 0, v[50:51]
	v_lshl_add_u64 v[42:43], v[156:157], 0, s[18:19]
	global_store_dwordx4 v[38:39], v[34:37], off
	v_lshl_add_u64 v[44:45], v[42:43], 2, s[0:1]
	v_lshlrev_b32_e32 v184, 2, v156
	v_readlane_b32 s100, v253, 58
	v_readlane_b32 s101, v253, 59
	s_nop 1
	s_add_u32 s100, s100, 0x140000
	s_addc_u32 s101, s101, 0
	global_load_dwordx4 v[176:179], v184, s[100:101] offset:16
	global_load_dwordx4 v[180:183], v184, s[100:101] offset:0
	global_load_dwordx4 v[188:191], v184, s[100:101] offset:528
	global_load_dwordx4 v[192:195], v184, s[100:101] offset:512
	s_add_u32 s100, s100, 0x20000
	s_addc_u32 s101, s101, 0
	global_load_dwordx4 v[196:199], v184, s[100:101] offset:16
	global_load_dwordx4 v[200:203], v184, s[100:101] offset:0
	global_load_dwordx4 v[204:207], v184, s[100:101] offset:528
	global_load_dwordx4 v[218:221], v184, s[100:101] offset:512
	s_waitcnt vmcnt(0)
	s_mov_b64 s[18:19], 0x58000
	v_pk_mul_f32 v[36:37], v[178:179], s[60:61] op_sel_hi:[1,0]
	v_pk_mul_f32 v[40:41], v[182:183], s[60:61] op_sel_hi:[1,0]
	v_pk_mul_f32 v[38:39], v[180:181], s[60:61] op_sel_hi:[1,0]
	v_pk_mul_f32 v[34:35], v[176:177], s[60:61] op_sel_hi:[1,0]
	v_pk_fma_f32 v[32:33], v[32:33], v[152:153], v[40:41]
	v_pk_fma_f32 v[30:31], v[30:31], v[154:155], v[38:39]
	v_pk_fma_f32 v[36:37], v[28:29], v[148:149], v[36:37]
	v_pk_fma_f32 v[28:29], v[26:27], v[150:151], v[34:35]
	v_lshlrev_b64 v[34:35], 1, v[42:43]
	v_cvt_pk_bf16_f32 v26, v30, v31
	v_cvt_pk_bf16_f32 v27, v32, v33
	v_cvt_pk_bf16_f32 v28, v28, v29
	v_cvt_pk_bf16_f32 v29, v36, v37
	v_lshl_add_u64 v[30:31], s[50:51], 0, v[34:35]
	global_store_dwordx4 v[30:31], v[26:29], off
	s_nop 0
	v_or_b32_e32 v34, 0x100, v34
	v_pk_mul_f32 v[28:29], v[190:191], s[60:61] op_sel_hi:[1,0]
	v_pk_mul_f32 v[32:33], v[194:195], s[60:61] op_sel_hi:[1,0]
	v_pk_mul_f32 v[30:31], v[192:193], s[60:61] op_sel_hi:[1,0]
	v_pk_mul_f32 v[26:27], v[188:189], s[60:61] op_sel_hi:[1,0]
	v_pk_fma_f32 v[24:25], v[24:25], v[144:145], v[32:33]
	v_pk_fma_f32 v[22:23], v[22:23], v[146:147], v[30:31]
	v_pk_fma_f32 v[28:29], v[20:21], v[140:141], v[28:29]
	v_pk_fma_f32 v[20:21], v[18:19], v[142:143], v[26:27]
	v_cvt_pk_bf16_f32 v18, v22, v23
	v_cvt_pk_bf16_f32 v19, v24, v25
	v_cvt_pk_bf16_f32 v20, v20, v21
	v_cvt_pk_bf16_f32 v21, v28, v29
	v_lshl_add_u64 v[22:23], s[50:51], 0, v[34:35]
	v_lshl_add_u64 v[26:27], v[156:157], 0, s[18:19]
	global_store_dwordx4 v[22:23], v[18:21], off
	v_lshl_add_u64 v[28:29], v[26:27], 2, s[0:1]
	s_mov_b64 s[0:1], -1
	v_pk_mul_f32 v[20:21], v[198:199], s[60:61] op_sel_hi:[1,0]
	v_pk_mul_f32 v[24:25], v[202:203], s[60:61] op_sel_hi:[1,0]
	v_pk_mul_f32 v[22:23], v[200:201], s[60:61] op_sel_hi:[1,0]
	v_pk_mul_f32 v[18:19], v[196:197], s[60:61] op_sel_hi:[1,0]
	v_pk_fma_f32 v[16:17], v[16:17], v[152:153], v[24:25]
	v_pk_fma_f32 v[14:15], v[14:15], v[154:155], v[22:23]
	v_pk_fma_f32 v[20:21], v[12:13], v[148:149], v[20:21]
	v_pk_fma_f32 v[12:13], v[10:11], v[150:151], v[18:19]
	v_lshlrev_b64 v[18:19], 1, v[26:27]
	v_cvt_pk_bf16_f32 v10, v14, v15
	v_cvt_pk_bf16_f32 v11, v16, v17
	v_cvt_pk_bf16_f32 v12, v12, v13
	v_cvt_pk_bf16_f32 v13, v20, v21
	v_lshl_add_u64 v[14:15], s[50:51], 0, v[18:19]
	global_store_dwordx4 v[14:15], v[10:13], off
	s_nop 0
	v_or_b32_e32 v18, 0x100, v18
	v_pk_mul_f32 v[12:13], v[206:207], s[60:61] op_sel_hi:[1,0]
	v_pk_mul_f32 v[16:17], v[220:221], s[60:61] op_sel_hi:[1,0]
	v_pk_mul_f32 v[14:15], v[218:219], s[60:61] op_sel_hi:[1,0]
	v_pk_mul_f32 v[10:11], v[204:205], s[60:61] op_sel_hi:[1,0]
	v_pk_fma_f32 v[8:9], v[8:9], v[144:145], v[16:17]
	v_pk_fma_f32 v[6:7], v[6:7], v[146:147], v[14:15]
	v_pk_fma_f32 v[12:13], v[4:5], v[140:141], v[12:13]
	v_pk_fma_f32 v[4:5], v[2:3], v[142:143], v[10:11]
	v_cvt_pk_bf16_f32 v2, v6, v7
	v_cvt_pk_bf16_f32 v3, v8, v9
	v_cvt_pk_bf16_f32 v4, v4, v5
	v_cvt_pk_bf16_f32 v5, v12, v13
	v_lshl_add_u64 v[6:7], s[50:51], 0, v[18:19]
	global_store_dwordx4 v[6:7], v[2:5], off
	s_cbranch_vccnz .LBB0_838
	s_andn2_b64 vcc, exec, s[6:7]
	s_cbranch_vccnz .LBB0_837
	s_barrier
	s_branch .LBB0_837
